# attention softmax max/sum and norm cross-lane reductions: ds_bpermute replaced by v_permlane16/32_swap (xor 16/32) and DPP quad_perm (xor 1/2)
# baseline (speedup 1.0000x reference)
.LBB0_414:
	v_add_u32_e32 v90, v187, v188
	ds_read_b128 v[34:37], v90
	ds_read_b128 v[38:41], v90 offset:64
	s_cmp_eq_u32 s24, 0
	s_cselect_b64 s[0:1], -1, 0
	v_cndmask_b32_e64 v53, v21, v5, s[0:1]
	v_cndmask_b32_e64 v52, v20, v4, s[0:1]
	v_cndmask_b32_e64 v51, v19, v3, s[0:1]
	v_cndmask_b32_e64 v50, v18, v2, s[0:1]
	v_cndmask_b32_e64 v149, v25, v9, s[0:1]
	v_cndmask_b32_e64 v148, v24, v8, s[0:1]
	s_waitcnt lgkmcnt(1)
	v_mfma_f32_16x16x32_bf16 v[34:37], v[34:37], v[50:53], 0
	v_cndmask_b32_e64 v147, v23, v7, s[0:1]
	v_cndmask_b32_e64 v146, v22, v6, s[0:1]
	global_load_dword v121, v[96:97], off
	ds_read_b128 v[42:45], v90 offset:39232
	s_waitcnt lgkmcnt(1)
	v_mfma_f32_16x16x32_bf16 v[150:153], v[38:41], v[146:149], v[34:37]
	ds_read_b128 v[38:41], v90 offset:4416
	ds_read_b128 v[46:49], v90 offset:43584
	ds_read_b128 v[202:205], v90 offset:47936
	ds_read_b128 v[34:37], v90 offset:4352
	s_waitcnt lgkmcnt(0)
	v_mfma_f32_16x16x32_bf16 v[34:37], v[34:37], v[50:53], 0
	s_waitcnt vmcnt(0)
	v_mul_f32_e32 v75, 0x3fb8aa3b, v121
	v_mfma_f32_16x16x32_bf16 v[154:157], v[38:41], v[146:149], v[34:37]
	ds_read_b128 v[38:41], v90 offset:8768
	s_nop 3
	ds_read_b128 v[34:37], v90 offset:8704
	s_waitcnt lgkmcnt(0)
	v_mfma_f32_16x16x32_bf16 v[34:37], v[34:37], v[50:53], 0
	v_mfma_f32_16x16x32_bf16 v[158:161], v[38:41], v[146:149], v[34:37]
	ds_read_b128 v[38:41], v90 offset:13120
	s_nop 5
	ds_read_b128 v[34:37], v90 offset:13056
	s_waitcnt lgkmcnt(0)
	v_mfma_f32_16x16x32_bf16 v[34:37], v[34:37], v[50:53], 0
	v_mfma_f32_16x16x32_bf16 v[70:73], v[38:41], v[146:149], v[34:37]
	ds_read_b128 v[38:41], v90 offset:17472
	s_nop 5
	ds_read_b128 v[34:37], v90 offset:17408
	s_waitcnt lgkmcnt(0)
	v_mfma_f32_16x16x32_bf16 v[34:37], v[34:37], v[50:53], 0
	v_add_f32_e64 v70, v86, v70
	v_add_f32_e64 v71, v87, v71
	v_mfma_f32_16x16x32_bf16 v[66:69], v[38:41], v[146:149], v[34:37]
	ds_read_b128 v[38:41], v90 offset:21824
	s_nop 3
	ds_read_b128 v[34:37], v90 offset:21760
	s_waitcnt lgkmcnt(0)
	v_mfma_f32_16x16x32_bf16 v[34:37], v[34:37], v[50:53], 0
	v_add_f32_e64 v66, v88, v66
	v_add_f32_e64 v67, v89, v67
	v_mfma_f32_16x16x32_bf16 v[62:65], v[38:41], v[146:149], v[34:37]
	ds_read_b128 v[38:41], v90 offset:26176
	s_nop 3
	ds_read_b128 v[34:37], v90 offset:26112
	s_waitcnt lgkmcnt(0)
	v_mfma_f32_16x16x32_bf16 v[34:37], v[34:37], v[50:53], 0
	v_add_f32_e64 v62, v124, v62
	v_add_f32_e64 v63, v125, v63
	v_mfma_f32_16x16x32_bf16 v[58:61], v[38:41], v[146:149], v[34:37]
	ds_read_b128 v[38:41], v90 offset:30528
	s_nop 3
	ds_read_b128 v[34:37], v90 offset:30464
	s_waitcnt lgkmcnt(0)
	v_mfma_f32_16x16x32_bf16 v[34:37], v[34:37], v[50:53], 0
	v_add_f32_e64 v58, v128, v58
	v_add_f32_e64 v59, v129, v59
	v_mfma_f32_16x16x32_bf16 v[54:57], v[38:41], v[146:149], v[34:37]
	ds_read_b128 v[38:41], v90 offset:34880
	s_nop 3
	ds_read_b128 v[34:37], v90 offset:34816
	s_waitcnt lgkmcnt(0)
	v_mfma_f32_16x16x32_bf16 v[34:37], v[34:37], v[50:53], 0
	v_add_f32_e64 v54, v132, v54
	v_add_f32_e64 v55, v133, v55
	v_mfma_f32_16x16x32_bf16 v[34:37], v[38:41], v[146:149], v[34:37]
	ds_read_b128 v[38:41], v90 offset:39168
	s_waitcnt lgkmcnt(0)
	v_mfma_f32_16x16x32_bf16 v[38:41], v[38:41], v[50:53], 0
	s_nop 4
	v_add_f32_e64 v34, v136, v34
	v_add_f32_e64 v35, v137, v35
	v_mfma_f32_16x16x32_bf16 v[38:41], v[42:45], v[146:149], v[38:41]
	ds_read_b128 v[42:45], v90 offset:43520
	s_waitcnt lgkmcnt(0)
	v_mfma_f32_16x16x32_bf16 v[42:45], v[42:45], v[50:53], 0
	s_nop 4
	v_add_f32_e64 v40, v40, 0
	v_add_f32_e64 v41, v41, 0
	v_pk_add_f32 v[38:39], v[38:39], 0 op_sel_hi:[1,0]
	v_mfma_f32_16x16x32_bf16 v[42:45], v[46:49], v[146:149], v[42:45]
	ds_read_b128 v[46:49], v90 offset:47872
	s_waitcnt lgkmcnt(0)
	v_mfma_f32_16x16x32_bf16 v[46:49], v[46:49], v[50:53], 0
	s_nop 4
	v_add_f32_e64 v44, v44, 0
	v_add_f32_e64 v45, v45, 0
	v_pk_add_f32 v[42:43], v[42:43], 0 op_sel_hi:[1,0]
	v_mfma_f32_16x16x32_bf16 v[46:49], v[202:205], v[146:149], v[46:49]
	ds_read_b128 v[202:205], v90 offset:52224
	s_waitcnt lgkmcnt(0)
	v_mfma_f32_16x16x32_bf16 v[50:53], v[202:205], v[50:53], 0
	ds_read_b128 v[202:205], v90 offset:52288
	s_nop 3
	v_pk_add_f32 v[48:49], v[48:49], 0 op_sel_hi:[1,0]
	v_pk_add_f32 v[46:47], v[46:47], 0 op_sel_hi:[1,0]
	s_waitcnt lgkmcnt(0)
	v_mfma_f32_16x16x32_bf16 v[50:53], v[202:205], v[146:149], v[50:53]
	v_add_f32_e64 v146, v152, 0
	v_add_f32_e64 v147, v153, 0
	v_pk_add_f32 v[148:149], v[150:151], 0 op_sel_hi:[1,0]
	v_max_f32_e32 v81, v146, v147
	v_max_f32_e32 v77, v148, v149
	v_max3_f32 v75, v75, v77, v81
	v_mov_b32_e32 v77, v76
	v_pk_add_f32 v[150:151], v[76:77], v[156:157]
	v_pk_add_f32 v[152:153], v[78:79], v[154:155]
	v_max_f32_e32 v85, v150, v151
	v_max_f32_e32 v81, v152, v153
	v_max3_f32 v75, v75, v81, v85
	v_mov_b32_e32 v81, v80
	v_pk_add_f32 v[154:155], v[80:81], v[160:161]
	v_pk_add_f32 v[156:157], v[82:83], v[158:159]
	v_max_f32_e32 v123, v154, v155
	v_max_f32_e32 v85, v156, v157
	v_max3_f32 v75, v75, v85, v123
	v_mov_b32_e32 v85, v84
	v_pk_add_f32 v[72:73], v[84:85], v[72:73]
	v_max_f32_e32 v123, v70, v71
	v_max_f32_e32 v127, v72, v73
	v_max3_f32 v123, v75, v123, v127
	v_mov_b32_e32 v75, v74
	v_pk_add_f32 v[68:69], v[74:75], v[68:69]
	v_max_f32_e32 v127, v66, v67
	v_max_f32_e32 v131, v68, v69
	v_max3_f32 v127, v123, v127, v131
	v_mov_b32_e32 v123, v122
	v_pk_add_f32 v[64:65], v[122:123], v[64:65]
	v_max_f32_e32 v131, v62, v63
	v_max_f32_e32 v135, v64, v65
	v_max3_f32 v131, v127, v131, v135
	v_mov_b32_e32 v127, v126
	v_pk_add_f32 v[60:61], v[126:127], v[60:61]
	v_max_f32_e32 v135, v58, v59
	v_max_f32_e32 v158, v60, v61
	v_max3_f32 v135, v131, v135, v158
	v_mov_b32_e32 v131, v130
	v_pk_add_f32 v[56:57], v[130:131], v[56:57]
	v_max_f32_e32 v158, v54, v55
	v_max_f32_e32 v159, v56, v57
	v_max3_f32 v158, v135, v158, v159
	v_mov_b32_e32 v135, v134
	v_pk_add_f32 v[36:37], v[134:135], v[36:37]
	v_max_f32_e32 v159, v34, v35
	v_max_f32_e32 v160, v36, v37
	v_max3_f32 v158, v158, v159, v160
	v_max_f32_e32 v159, v38, v39
	v_max_f32_e32 v160, v40, v41
	v_max3_f32 v158, v158, v159, v160
	v_max_f32_e32 v159, v42, v43
	v_max_f32_e32 v160, v44, v45
	v_max3_f32 v158, v158, v159, v160
	v_max_f32_e32 v159, v46, v47
	v_max_f32_e32 v160, v48, v49
	v_pk_add_f32 v[52:53], v[52:53], 0 op_sel_hi:[1,0]
	v_pk_add_f32 v[50:51], v[50:51], 0 op_sel_hi:[1,0]
	v_max3_f32 v158, v158, v159, v160
	v_max_f32_e32 v159, v50, v51
	v_max_f32_e32 v160, v52, v53
	v_max3_f32 v158, v158, v159, v160
	v_mov_b32_e32 v159, v158
	s_nop 1
	v_permlane16_swap_b32_e32 v159, v158
	s_nop 1
	s_waitcnt lgkmcnt(0)
	v_max_f32_e32 v159, v159, v159
	v_max_f32_e32 v158, v158, v159
	v_mov_b32_e32 v159, v158
	s_nop 1
	v_permlane32_swap_b32_e32 v159, v158
	s_nop 1
	s_waitcnt lgkmcnt(0)
	v_max_f32_e32 v159, v159, v159
	v_max_f32_e32 v210, v158, v159
	v_sub_f32_e32 v149, v149, v210
	v_sub_f32_e32 v146, v146, v210
	v_sub_f32_e32 v148, v148, v210
	v_exp_f32_e32 v158, v149
	v_exp_f32_e32 v149, v146
	v_sub_f32_e32 v146, v147, v210
	v_exp_f32_e32 v148, v148
	v_exp_f32_e32 v159, v146
	v_sub_f32_e32 v70, v70, v210
	v_sub_f32_e32 v67, v67, v210
	v_sub_f32_e32 v66, v66, v210
	v_pk_add_f32 v[146:147], v[148:149], v[158:159]
	v_exp_f32_e32 v66, v66
	v_add_f32_e32 v146, v146, v147
	v_add_f32_e32 v147, 0, v146
	v_sub_f32_e32 v146, v152, v210
	v_exp_f32_e32 v152, v146
	v_sub_f32_e32 v146, v153, v210
	v_exp_f32_e32 v160, v146
	v_sub_f32_e32 v146, v150, v210
	v_exp_f32_e32 v153, v146
	v_sub_f32_e32 v146, v151, v210
	v_exp_f32_e32 v161, v146
	v_sub_f32_e32 v146, v156, v210
	v_exp_f32_e32 v220, v146
	v_sub_f32_e32 v146, v157, v210
	v_pk_add_f32 v[150:151], v[152:153], v[160:161]
	v_exp_f32_e32 v221, v146
	v_sub_f32_e32 v146, v154, v210
	v_exp_f32_e32 v154, v70
	v_sub_f32_e32 v70, v71, v210
	v_pk_add_f32 v[150:151], v[150:151], v[150:151] op_sel_hi:[0,1]
	v_exp_f32_e32 v222, v146
	v_sub_f32_e32 v146, v155, v210
	v_exp_f32_e32 v156, v70
	v_sub_f32_e32 v70, v72, v210
	v_exp_f32_e32 v223, v146
	v_exp_f32_e32 v150, v70
	v_sub_f32_e32 v70, v73, v210
	v_exp_f32_e32 v146, v70
	v_add_f32_e32 v155, v220, v221
	v_add_f32_e32 v157, v222, v223
	v_pk_add_f32 v[70:71], v[154:155], v[156:157]
	v_pk_add_f32 v[72:73], v[150:151], v[146:147]
	v_sub_f32_e32 v62, v62, v210
	v_pk_add_f32 v[70:71], v[70:71], v[72:73]
	v_exp_f32_e32 v72, v67
	v_sub_f32_e32 v67, v68, v210
	v_sub_f32_e32 v68, v69, v210
	v_exp_f32_e32 v67, v67
	v_exp_f32_e32 v73, v68
	v_exp_f32_e32 v147, v62
	v_sub_f32_e32 v62, v63, v210
	v_exp_f32_e32 v151, v62
	v_sub_f32_e32 v62, v64, v210
	v_exp_f32_e32 v155, v62
	v_sub_f32_e32 v62, v65, v210
	v_sub_f32_e32 v58, v58, v210
	v_pk_add_f32 v[68:69], v[66:67], v[72:73]
	v_exp_f32_e32 v157, v62
	v_exp_f32_e32 v62, v58
	v_sub_f32_e32 v58, v59, v210
	v_pk_add_f32 v[68:69], v[68:69], v[68:69] op_sel_hi:[0,1]
	v_exp_f32_e32 v64, v58
	v_sub_f32_e32 v58, v60, v210
	v_pk_add_f32 v[70:71], v[70:71], v[70:71] op_sel_hi:[0,1]
	v_exp_f32_e32 v68, v58
	v_sub_f32_e32 v58, v61, v210
	v_exp_f32_e32 v70, v58
	v_add_f32_e32 v63, v147, v151
	v_add_f32_e32 v65, v155, v157
	v_pk_add_f32 v[58:59], v[62:63], v[64:65]
	v_pk_add_f32 v[60:61], v[68:69], v[70:71]
	v_sub_f32_e32 v55, v55, v210
	v_pk_add_f32 v[58:59], v[58:59], v[60:61]
	v_sub_f32_e32 v54, v54, v210
	v_exp_f32_e32 v60, v55
	v_sub_f32_e32 v55, v56, v210
	v_sub_f32_e32 v56, v57, v210
	v_sub_f32_e32 v34, v34, v210
	v_exp_f32_e32 v54, v54
	v_exp_f32_e32 v55, v55
	v_exp_f32_e32 v61, v56
	v_exp_f32_e32 v63, v34
	v_sub_f32_e32 v34, v35, v210
	v_exp_f32_e32 v65, v34
	v_sub_f32_e32 v34, v36, v210
	v_exp_f32_e32 v69, v34
	v_sub_f32_e32 v34, v37, v210
	v_exp_f32_e32 v71, v34
	v_sub_f32_e32 v34, v38, v210
	v_pk_add_f32 v[56:57], v[54:55], v[60:61]
	v_exp_f32_e32 v202, v34
	v_sub_f32_e32 v34, v39, v210
	v_pk_add_f32 v[56:57], v[56:57], v[56:57] op_sel_hi:[0,1]
	v_exp_f32_e32 v204, v34
	v_sub_f32_e32 v34, v40, v210
	v_pk_add_f32 v[58:59], v[58:59], v[58:59] op_sel_hi:[0,1]
	v_exp_f32_e32 v56, v34
	v_sub_f32_e32 v34, v41, v210
	v_exp_f32_e32 v58, v34
	v_add_f32_e32 v203, v63, v65
	v_add_f32_e32 v205, v69, v71
	v_pk_add_f32 v[34:35], v[202:203], v[204:205]
	v_pk_add_f32 v[36:37], v[56:57], v[58:59]
	s_nop 0
	v_pk_add_f32 v[34:35], v[34:35], v[36:37]
	s_nop 0
	v_pk_add_f32 v[206:207], v[34:35], v[34:35] op_sel_hi:[0,1]
	v_sub_f32_e32 v34, v42, v210
	v_exp_f32_e32 v208, v34
	v_sub_f32_e32 v34, v43, v210
	v_exp_f32_e32 v212, v34
	v_sub_f32_e32 v34, v44, v210
	v_exp_f32_e32 v209, v34
	v_sub_f32_e32 v34, v45, v210
	v_exp_f32_e32 v213, v34
	s_nop 0
	v_pk_add_f32 v[34:35], v[208:209], v[212:213]
	s_nop 0
	v_pk_add_f32 v[214:215], v[34:35], v[34:35] op_sel_hi:[0,1]
	v_sub_f32_e32 v34, v46, v210
	v_exp_f32_e32 v57, v34
	v_sub_f32_e32 v34, v47, v210
	v_exp_f32_e32 v59, v34
	v_sub_f32_e32 v34, v48, v210
	v_exp_f32_e32 v203, v34
	v_sub_f32_e32 v34, v49, v210
	v_exp_f32_e32 v205, v34
	v_sub_f32_e32 v34, v50, v210
	v_exp_f32_e32 v216, v34
	v_sub_f32_e32 v34, v51, v210
	v_exp_f32_e32 v218, v34
	v_sub_f32_e32 v34, v52, v210
	v_exp_f32_e32 v214, v34
	v_sub_f32_e32 v34, v53, v210
	v_exp_f32_e32 v206, v34
	v_add_f32_e32 v217, v57, v59
	v_add_f32_e32 v219, v203, v205
	v_pk_add_f32 v[34:35], v[216:217], v[218:219]
	v_pk_add_f32 v[36:37], v[214:215], v[206:207]
	s_nop 0
	v_pk_add_f32 v[34:35], v[34:35], v[36:37]
	s_nop 0
	v_add_f32_e32 v34, v34, v35
	v_mov_b32_e32 v35, v34
	s_nop 1
	v_permlane16_swap_b32_e32 v35, v34
	s_nop 1
	s_waitcnt lgkmcnt(0)
	v_add_f32_e32 v34, v34, v35
	v_mov_b32_e32 v35, v34
	s_nop 1
	v_permlane32_swap_b32_e32 v35, v34
	s_nop 1
	s_waitcnt lgkmcnt(0)
	v_add_f32_e32 v34, v34, v35
	v_fma_f32 v35, v121, s65, -v210
	v_exp_f32_e32 v35, v35
	s_nop 0
	v_add_f32_e32 v121, v35, v34
	v_cvt_pk_bf16_f32 v34, v148, v158
	v_cvt_pk_bf16_f32 v35, v149, v159
	v_cvt_pk_bf16_f32 v36, v152, v160
	v_cvt_pk_bf16_f32 v37, v153, v161
	v_cvt_pk_bf16_f32 v38, v220, v221
	v_cvt_pk_bf16_f32 v39, v222, v223
	v_cvt_pk_bf16_f32 v40, v154, v156
	v_cvt_pk_bf16_f32 v41, v150, v146
	v_cvt_pk_bf16_f32 v42, v66, v72
	v_cvt_pk_bf16_f32 v43, v67, v73
	v_cvt_pk_bf16_f32 v44, v147, v151
	v_cvt_pk_bf16_f32 v45, v155, v157
	v_cvt_pk_bf16_f32 v46, v62, v64
	v_div_scale_f32 v62, s[26:27], v121, v121, 1.0
	v_cvt_pk_bf16_f32 v47, v68, v70
	v_cvt_pk_bf16_f32 v48, v54, v60
	v_cvt_pk_bf16_f32 v49, v55, v61
	v_cvt_pk_bf16_f32 v50, v63, v65
	v_rcp_f32_e32 v63, v62
	v_add_u32_e32 v70, v189, v164
	v_cvt_pk_bf16_f32 v51, v69, v71
	v_add_u32_e32 v71, 0xd800, v70
	v_fma_f32 v64, -v62, v63, 1.0
	v_fmac_f32_e32 v63, v64, v63
	v_div_scale_f32 v64, vcc, 1.0, v121, 1.0
	v_mul_f32_e32 v65, v64, v63
	v_fma_f32 v66, -v62, v65, v64
	v_fmac_f32_e32 v65, v66, v63
	v_fma_f32 v62, -v62, v65, v64
	v_div_fmas_f32 v62, v62, v63, v65
	v_cvt_pk_bf16_f32 v52, v202, v204
	v_cvt_pk_bf16_f32 v53, v56, v58
	v_cvt_pk_bf16_f32 v54, v208, v212
	v_cvt_pk_bf16_f32 v55, v209, v213
	v_cvt_pk_bf16_f32 v56, v57, v59
	v_cvt_pk_bf16_f32 v57, v203, v205
	v_cvt_pk_bf16_f32 v58, v216, v218
	v_cvt_pk_bf16_f32 v59, v214, v206
	v_cvt_pk_bf16_f32 v60, v91, v91
	v_cvt_pk_bf16_f32 v61, v91, v91
	v_div_fixup_f32 v72, v62, v121, 1.0
	ds_read2_b64 v[62:65], v71 offset0:160 offset1:164
	ds_read2_b64 v[66:69], v71 offset0:168 offset1:172
	s_waitcnt lgkmcnt(1)
	v_mfma_f32_16x16x32_bf16 v[62:65], v[62:65], v[34:37], 0
	v_add_u32_e32 v70, 0xf800, v70
	ds_read_b128 v[154:157], v90 offset:21952
	ds_read_b128 v[158:161], v90 offset:26304
	s_waitcnt lgkmcnt(2)
	v_mfma_f32_16x16x32_bf16 v[62:65], v[66:69], v[38:41], v[62:65]
	ds_read2_b64 v[66:69], v71 offset0:176 offset1:180
	ds_read_b128 v[202:205], v90 offset:30656
	ds_read_b128 v[206:209], v90 offset:35008
	s_waitcnt lgkmcnt(2)
	v_mfma_f32_16x16x32_bf16 v[62:65], v[66:69], v[42:45], v[62:65]
	ds_read2_b64 v[66:69], v71 offset0:184 offset1:188
	ds_read_b128 v[212:215], v90 offset:39360
	ds_read_b128 v[216:219], v90 offset:43712
	s_waitcnt lgkmcnt(2)
	v_mfma_f32_16x16x32_bf16 v[62:65], v[66:69], v[46:49], v[62:65]
	ds_read2_b64 v[66:69], v71 offset0:192 offset1:196
	ds_read_b128 v[220:223], v90 offset:48064
	s_waitcnt lgkmcnt(1)
	v_mfma_f32_16x16x32_bf16 v[62:65], v[66:69], v[50:53], v[62:65]
	ds_read2_b64 v[66:69], v71 offset0:200 offset1:204
	s_waitcnt lgkmcnt(0)
	v_mfma_f32_16x16x32_bf16 v[62:65], v[66:69], v[54:57], v[62:65]
	ds_read2_b64 v[66:69], v71 offset0:208 offset1:212
	s_waitcnt lgkmcnt(0)
	v_mfma_f32_16x16x32_bf16 v[62:65], v[66:69], v[58:61], v[62:65]
	ds_read2_b64 v[66:69], v70 offset0:88 offset1:92
	s_nop 6
	v_pk_mul_f32 v[146:147], v[72:73], v[64:65] op_sel_hi:[0,1]
	v_pk_mul_f32 v[148:149], v[72:73], v[62:63] op_sel_hi:[0,1]
	ds_read2_b64 v[62:65], v70 offset0:80 offset1:84
	s_waitcnt lgkmcnt(0)
	v_mfma_f32_16x16x32_bf16 v[62:65], v[62:65], v[34:37], 0
	v_mfma_f32_16x16x32_bf16 v[62:65], v[66:69], v[38:41], v[62:65]
	ds_read2_b64 v[66:69], v70 offset0:96 offset1:100
	s_waitcnt lgkmcnt(0)
	v_mfma_f32_16x16x32_bf16 v[62:65], v[66:69], v[42:45], v[62:65]
	ds_read2_b64 v[66:69], v70 offset0:104 offset1:108
	s_waitcnt lgkmcnt(0)
	v_mfma_f32_16x16x32_bf16 v[62:65], v[66:69], v[46:49], v[62:65]
	ds_read2_b64 v[66:69], v70 offset0:112 offset1:116
	s_waitcnt lgkmcnt(0)
	v_mfma_f32_16x16x32_bf16 v[62:65], v[66:69], v[50:53], v[62:65]
	ds_read2_b64 v[66:69], v70 offset0:120 offset1:124
	s_waitcnt lgkmcnt(0)
	v_mfma_f32_16x16x32_bf16 v[62:65], v[66:69], v[54:57], v[62:65]
	ds_read2_b64 v[66:69], v70 offset0:128 offset1:132
	v_add_u32_e32 v70, 0x3800, v190
	ds_read2_b64 v[150:153], v70 offset0:104 offset1:108
	s_waitcnt lgkmcnt(1)
	v_mfma_f32_16x16x32_bf16 v[64:67], v[66:69], v[58:61], v[62:65]
	s_nop 7
	v_pk_mul_f32 v[62:63], v[72:73], v[66:67] op_sel_hi:[0,1]
	ds_read2_b64 v[66:69], v70 offset0:96 offset1:100
	s_waitcnt lgkmcnt(0)
	v_mfma_f32_16x16x32_bf16 v[66:69], v[66:69], v[34:37], 0
	v_mul_f32_e64 v64, v72, v64
	v_mul_f32_e64 v65, v72, v65
	v_mfma_f32_16x16x32_bf16 v[66:69], v[150:153], v[38:41], v[66:69]
	ds_read2_b64 v[150:153], v70 offset0:112 offset1:116
	s_waitcnt lgkmcnt(0)
	v_mfma_f32_16x16x32_bf16 v[66:69], v[150:153], v[42:45], v[66:69]
	ds_read2_b64 v[150:153], v70 offset0:120 offset1:124
	s_waitcnt lgkmcnt(0)
	v_mfma_f32_16x16x32_bf16 v[66:69], v[150:153], v[46:49], v[66:69]
	ds_read2_b64 v[150:153], v70 offset0:128 offset1:132
	s_waitcnt lgkmcnt(0)
	v_mfma_f32_16x16x32_bf16 v[66:69], v[150:153], v[50:53], v[66:69]
	ds_read2_b64 v[150:153], v70 offset0:136 offset1:140
	s_waitcnt lgkmcnt(0)
	v_mfma_f32_16x16x32_bf16 v[66:69], v[150:153], v[54:57], v[66:69]
	ds_read2_b64 v[150:153], v70 offset0:144 offset1:148
	v_add_u32_e32 v70, 0x5800, v190
	s_waitcnt lgkmcnt(0)
	v_mfma_f32_16x16x32_bf16 v[66:69], v[150:153], v[58:61], v[66:69]
	ds_read2_b64 v[150:153], v70 offset0:16 offset1:20
	s_nop 6
	v_pk_mul_f32 v[66:67], v[72:73], v[66:67] op_sel_hi:[0,1]
	s_waitcnt lgkmcnt(0)
	v_mfma_f32_16x16x32_bf16 v[34:37], v[150:153], v[34:37], 0
	ds_read2_b64 v[150:153], v70 offset0:24 offset1:28
	v_pk_mul_f32 v[68:69], v[72:73], v[68:69] op_sel_hi:[0,1]
	s_waitcnt lgkmcnt(0)
	v_mfma_f32_16x16x32_bf16 v[34:37], v[150:153], v[38:41], v[34:37]
	ds_read2_b64 v[38:41], v70 offset0:32 offset1:36
	ds_read_b128 v[150:153], v90 offset:17600
	s_waitcnt lgkmcnt(1)
	v_mfma_f32_16x16x32_bf16 v[34:37], v[38:41], v[42:45], v[34:37]
	ds_read2_b64 v[38:41], v70 offset0:40 offset1:44
	ds_read_b128 v[42:45], v90 offset:128
	s_waitcnt lgkmcnt(1)
	v_mfma_f32_16x16x32_bf16 v[34:37], v[38:41], v[46:49], v[34:37]
	ds_read2_b64 v[38:41], v70 offset0:48 offset1:52
	ds_read_b128 v[46:49], v90 offset:192
	s_waitcnt lgkmcnt(1)
	v_mfma_f32_16x16x32_bf16 v[34:37], v[38:41], v[50:53], v[34:37]
	ds_read2_b64 v[38:41], v70 offset0:56 offset1:60
	ds_read_b128 v[50:53], v90 offset:4544
	s_waitcnt lgkmcnt(1)
	v_mfma_f32_16x16x32_bf16 v[34:37], v[38:41], v[54:57], v[34:37]
	ds_read2_b64 v[38:41], v70 offset0:64 offset1:68
	ds_read_b128 v[54:57], v90 offset:8896
	s_waitcnt lgkmcnt(1)
	v_mfma_f32_16x16x32_bf16 v[34:37], v[38:41], v[58:61], v[34:37]
	v_cndmask_b32_e64 v41, v33, v17, s[0:1]
	v_cndmask_b32_e64 v40, v32, v16, s[0:1]
	v_cndmask_b32_e64 v39, v31, v15, s[0:1]
	s_nop 4
	v_pk_mul_f32 v[70:71], v[72:73], v[36:37] op_sel_hi:[0,1]
	v_pk_mul_f32 v[72:73], v[72:73], v[34:35] op_sel_hi:[0,1]
	v_cndmask_b32_e64 v37, v29, v13, s[0:1]
	v_cndmask_b32_e64 v36, v28, v12, s[0:1]
	v_cndmask_b32_e64 v35, v27, v11, s[0:1]
	v_cndmask_b32_e64 v34, v26, v10, s[0:1]
	v_cndmask_b32_e64 v38, v30, v14, s[0:1]
	ds_read_b128 v[58:61], v90 offset:13248
	v_mfma_f32_16x16x32_bf16 v[42:45], v[42:45], v[34:37], 0
	v_mfma_f32_16x16x32_bf16 v[42:45], v[46:49], v[38:41], v[42:45]
	ds_read_b128 v[46:49], v90 offset:4480
	s_waitcnt lgkmcnt(0)
	v_mfma_f32_16x16x32_bf16 v[46:49], v[46:49], v[34:37], 0
	v_mfma_f32_16x16x32_bf16 v[46:49], v[50:53], v[38:41], v[46:49]
	ds_read_b128 v[50:53], v90 offset:8832
	s_waitcnt lgkmcnt(0)
	v_mfma_f32_16x16x32_bf16 v[50:53], v[50:53], v[34:37], 0
	v_mfma_f32_16x16x32_bf16 v[50:53], v[54:57], v[38:41], v[50:53]
	ds_read_b128 v[54:57], v90 offset:13184
	s_waitcnt lgkmcnt(0)
	v_mfma_f32_16x16x32_bf16 v[54:57], v[54:57], v[34:37], 0
	v_mfma_f32_16x16x32_bf16 v[54:57], v[58:61], v[38:41], v[54:57]
	ds_read_b128 v[58:61], v90 offset:17536
	s_waitcnt lgkmcnt(0)
	v_mfma_f32_16x16x32_bf16 v[58:61], v[58:61], v[34:37], 0
	v_mfma_f32_16x16x32_bf16 v[58:61], v[150:153], v[38:41], v[58:61]
	ds_read_b128 v[150:153], v90 offset:21888
	s_waitcnt lgkmcnt(0)
	v_mfma_f32_16x16x32_bf16 v[150:153], v[150:153], v[34:37], 0
	v_mfma_f32_16x16x32_bf16 v[150:153], v[154:157], v[38:41], v[150:153]
	ds_read_b128 v[154:157], v90 offset:26240
	s_waitcnt lgkmcnt(0)
	v_mfma_f32_16x16x32_bf16 v[154:157], v[154:157], v[34:37], 0
	v_mfma_f32_16x16x32_bf16 v[154:157], v[158:161], v[38:41], v[154:157]
	ds_read_b128 v[158:161], v90 offset:30592
	s_waitcnt lgkmcnt(0)
	v_mfma_f32_16x16x32_bf16 v[158:161], v[158:161], v[34:37], 0
	v_mfma_f32_16x16x32_bf16 v[158:161], v[202:205], v[38:41], v[158:161]
	ds_read_b128 v[202:205], v90 offset:34944
	s_waitcnt lgkmcnt(0)
	v_mfma_f32_16x16x32_bf16 v[202:205], v[202:205], v[34:37], 0
	v_mfma_f32_16x16x32_bf16 v[202:205], v[206:209], v[38:41], v[202:205]
	ds_read_b128 v[206:209], v90 offset:39296
	s_waitcnt lgkmcnt(0)
	v_mfma_f32_16x16x32_bf16 v[206:209], v[206:209], v[34:37], 0
	v_mfma_f32_16x16x32_bf16 v[206:209], v[212:215], v[38:41], v[206:209]
	ds_read_b128 v[212:215], v90 offset:43648
	s_waitcnt lgkmcnt(0)
	v_mfma_f32_16x16x32_bf16 v[212:215], v[212:215], v[34:37], 0
	v_mfma_f32_16x16x32_bf16 v[212:215], v[216:219], v[38:41], v[212:215]
	ds_read_b128 v[216:219], v90 offset:48000
	s_waitcnt lgkmcnt(0)
	v_mfma_f32_16x16x32_bf16 v[216:219], v[216:219], v[34:37], 0
	v_mfma_f32_16x16x32_bf16 v[216:219], v[220:223], v[38:41], v[216:219]
	ds_read_b128 v[220:223], v90 offset:52352
	s_waitcnt lgkmcnt(0)
	v_mfma_f32_16x16x32_bf16 v[34:37], v[220:223], v[34:37], 0
	ds_read_b128 v[220:223], v90 offset:52416
	global_load_dword v90, v[96:97], off offset:16
	s_waitcnt vmcnt(0)
	v_mul_f32_e32 v121, 0x3fb8aa3b, v90
	s_waitcnt lgkmcnt(0)
	v_mfma_f32_16x16x32_bf16 v[34:37], v[220:223], v[38:41], v[34:37]
	v_add_f32_e64 v38, v44, 0
	v_add_f32_e64 v39, v45, 0
	v_pk_add_f32 v[40:41], v[42:43], 0 op_sel_hi:[1,0]
	v_max_f32_e32 v43, v38, v39
	v_max_f32_e32 v42, v40, v41
	v_max3_f32 v121, v121, v42, v43
	v_pk_add_f32 v[42:43], v[76:77], v[48:49]
	v_pk_add_f32 v[44:45], v[78:79], v[46:47]
	v_max_f32_e32 v47, v42, v43
	v_max_f32_e32 v46, v44, v45
	v_max3_f32 v77, v121, v46, v47
	v_pk_add_f32 v[46:47], v[80:81], v[52:53]
	v_pk_add_f32 v[48:49], v[82:83], v[50:51]
	v_max_f32_e32 v51, v46, v47
	v_max_f32_e32 v50, v48, v49
	v_max3_f32 v77, v77, v50, v51
	v_pk_add_f32 v[50:51], v[84:85], v[56:57]
	v_pk_add_f32 v[52:53], v[86:87], v[54:55]
	v_max_f32_e32 v55, v50, v51
	v_max_f32_e32 v54, v52, v53
	v_max3_f32 v77, v77, v54, v55
	v_pk_add_f32 v[54:55], v[74:75], v[60:61]
	v_pk_add_f32 v[56:57], v[88:89], v[58:59]
	v_max_f32_e32 v59, v54, v55
	v_max_f32_e32 v58, v56, v57
	v_max3_f32 v75, v77, v58, v59
	v_pk_add_f32 v[58:59], v[122:123], v[152:153]
	v_pk_add_f32 v[60:61], v[124:125], v[150:151]
	v_max_f32_e32 v81, v58, v59
	v_max_f32_e32 v77, v60, v61
	v_pk_add_f32 v[150:151], v[126:127], v[156:157]
	v_pk_add_f32 v[152:153], v[128:129], v[154:155]
	v_max3_f32 v75, v75, v77, v81
	v_max_f32_e32 v77, v152, v153
	v_max_f32_e32 v81, v150, v151
	v_pk_add_f32 v[154:155], v[130:131], v[160:161]
	v_pk_add_f32 v[156:157], v[132:133], v[158:159]
	v_max3_f32 v75, v75, v77, v81
	v_max_f32_e32 v77, v156, v157
	v_max_f32_e32 v81, v154, v155
	v_pk_add_f32 v[158:159], v[134:135], v[204:205]
	v_pk_add_f32 v[160:161], v[136:137], v[202:203]
	v_max3_f32 v75, v75, v77, v81
	v_max_f32_e32 v77, v160, v161
	v_max_f32_e32 v81, v158, v159
	v_pk_add_f32 v[202:203], v[208:209], 0 op_sel_hi:[1,0]
	v_pk_add_f32 v[204:205], v[206:207], 0 op_sel_hi:[1,0]
	v_max3_f32 v75, v75, v77, v81
	v_max_f32_e32 v77, v204, v205
	v_max_f32_e32 v81, v202, v203
	v_pk_add_f32 v[206:207], v[214:215], 0 op_sel_hi:[1,0]
	v_pk_add_f32 v[208:209], v[212:213], 0 op_sel_hi:[1,0]
	v_max3_f32 v75, v75, v77, v81
	v_max_f32_e32 v77, v208, v209
	v_max_f32_e32 v81, v206, v207
	v_pk_add_f32 v[212:213], v[218:219], 0 op_sel_hi:[1,0]
	v_pk_add_f32 v[214:215], v[216:217], 0 op_sel_hi:[1,0]
	v_max3_f32 v75, v75, v77, v81
	v_max_f32_e32 v77, v214, v215
	v_max_f32_e32 v81, v212, v213
	v_pk_add_f32 v[36:37], v[36:37], 0 op_sel_hi:[1,0]
	v_pk_add_f32 v[34:35], v[34:35], 0 op_sel_hi:[1,0]
	v_max3_f32 v75, v75, v77, v81
	v_max_f32_e32 v77, v34, v35
	v_max_f32_e32 v81, v36, v37
	v_max3_f32 v75, v75, v77, v81
	v_mov_b32_e32 v77, v75
	s_nop 1
	v_permlane16_swap_b32_e32 v77, v75
	s_nop 1
	s_waitcnt lgkmcnt(0)
	v_max_f32_e32 v77, v77, v77
	v_max_f32_e32 v75, v75, v77
	v_mov_b32_e32 v77, v75
	s_nop 1
	v_permlane32_swap_b32_e32 v77, v75
	s_nop 1
	s_waitcnt lgkmcnt(0)
	v_max_f32_e32 v77, v77, v77
	v_max_f32_e32 v75, v75, v77
	v_sub_f32_e32 v41, v41, v75
	v_sub_f32_e32 v38, v38, v75
	v_sub_f32_e32 v40, v40, v75
	v_exp_f32_e32 v216, v41
	v_exp_f32_e32 v41, v38
	v_sub_f32_e32 v38, v39, v75
	v_exp_f32_e32 v40, v40
	v_exp_f32_e32 v217, v38
	v_sub_f32_e32 v34, v34, v75
	v_pk_add_f32 v[38:39], v[40:41], v[216:217]
	s_nop 0
	v_add_f32_e32 v38, v38, v39
	v_add_f32_e32 v219, 0, v38
	v_sub_f32_e32 v38, v44, v75
	v_exp_f32_e32 v44, v38
	v_sub_f32_e32 v38, v45, v75
	v_exp_f32_e32 v220, v38
	v_sub_f32_e32 v38, v42, v75
	v_exp_f32_e32 v45, v38
	v_sub_f32_e32 v38, v43, v75
	v_exp_f32_e32 v221, v38
	s_nop 0
	v_pk_add_f32 v[38:39], v[44:45], v[220:221]
	s_nop 0
	v_pk_add_f32 v[222:223], v[38:39], v[38:39] op_sel_hi:[0,1]
	v_sub_f32_e32 v38, v48, v75
	v_exp_f32_e32 v77, v38
	v_sub_f32_e32 v38, v49, v75
	v_exp_f32_e32 v81, v38
	v_sub_f32_e32 v38, v46, v75
	v_exp_f32_e32 v85, v38
	v_sub_f32_e32 v38, v47, v75
	v_exp_f32_e32 v121, v38
	v_sub_f32_e32 v38, v52, v75
	v_exp_f32_e32 v46, v38
	v_sub_f32_e32 v38, v53, v75
	v_exp_f32_e32 v48, v38
	v_sub_f32_e32 v38, v50, v75
	v_exp_f32_e32 v222, v38
	v_sub_f32_e32 v38, v51, v75
	v_exp_f32_e32 v218, v38
	v_add_f32_e32 v47, v77, v81
	v_add_f32_e32 v49, v85, v121
	v_pk_add_f32 v[38:39], v[46:47], v[48:49]
	v_pk_add_f32 v[42:43], v[222:223], v[218:219]
	s_nop 0
	v_pk_add_f32 v[38:39], v[38:39], v[42:43]
	s_nop 0
	v_pk_add_f32 v[52:53], v[38:39], v[38:39] op_sel_hi:[0,1]
	v_sub_f32_e32 v38, v56, v75
	v_exp_f32_e32 v50, v38
	v_sub_f32_e32 v38, v57, v75
	v_exp_f32_e32 v56, v38
	v_sub_f32_e32 v38, v54, v75
	v_exp_f32_e32 v51, v38
	v_sub_f32_e32 v38, v55, v75
	v_exp_f32_e32 v57, v38
	s_nop 0
	v_pk_add_f32 v[38:39], v[50:51], v[56:57]
	s_nop 0
	v_pk_add_f32 v[54:55], v[38:39], v[38:39] op_sel_hi:[0,1]
	v_sub_f32_e32 v38, v60, v75
	v_exp_f32_e32 v49, v38
	v_sub_f32_e32 v38, v61, v75
	v_exp_f32_e32 v123, v38
	v_sub_f32_e32 v38, v58, v75
	v_exp_f32_e32 v127, v38
	v_sub_f32_e32 v38, v59, v75
	v_exp_f32_e32 v131, v38
	v_sub_f32_e32 v38, v152, v75
	v_exp_f32_e32 v58, v38
	v_sub_f32_e32 v38, v153, v75
	v_exp_f32_e32 v60, v38
	v_sub_f32_e32 v38, v150, v75
	v_exp_f32_e32 v54, v38
	v_sub_f32_e32 v38, v151, v75
	v_exp_f32_e32 v52, v38
	v_add_f32_e32 v59, v49, v123
	v_add_f32_e32 v61, v127, v131
	v_pk_add_f32 v[38:39], v[58:59], v[60:61]
	v_pk_add_f32 v[42:43], v[54:55], v[52:53]
	s_nop 0
	v_pk_add_f32 v[38:39], v[38:39], v[42:43]
	s_nop 0
	v_pk_add_f32 v[150:151], v[38:39], v[38:39] op_sel_hi:[0,1]
	v_sub_f32_e32 v38, v156, v75
	v_exp_f32_e32 v152, v38
	v_sub_f32_e32 v38, v157, v75
	v_exp_f32_e32 v156, v38
	v_sub_f32_e32 v38, v154, v75
	v_exp_f32_e32 v153, v38
	v_sub_f32_e32 v38, v155, v75
	v_exp_f32_e32 v157, v38
	s_nop 0
	v_pk_add_f32 v[38:39], v[152:153], v[156:157]
	s_nop 0
	v_pk_add_f32 v[154:155], v[38:39], v[38:39] op_sel_hi:[0,1]
	v_sub_f32_e32 v38, v160, v75
	v_exp_f32_e32 v55, v38
	v_sub_f32_e32 v38, v161, v75
	v_exp_f32_e32 v59, v38
	v_sub_f32_e32 v38, v158, v75
	v_exp_f32_e32 v61, v38
	v_sub_f32_e32 v38, v159, v75
	v_exp_f32_e32 v135, v38
	v_sub_f32_e32 v38, v204, v75
	v_exp_f32_e32 v158, v38
	v_sub_f32_e32 v38, v205, v75
	v_exp_f32_e32 v160, v38
	v_sub_f32_e32 v38, v202, v75
	v_exp_f32_e32 v154, v38
	v_sub_f32_e32 v38, v203, v75
	v_exp_f32_e32 v150, v38
	v_add_f32_e32 v159, v55, v59
	v_add_f32_e32 v161, v61, v135
	v_pk_add_f32 v[38:39], v[158:159], v[160:161]
	v_pk_add_f32 v[42:43], v[154:155], v[150:151]
	s_nop 0
	v_pk_add_f32 v[38:39], v[38:39], v[42:43]
	s_nop 0
	v_pk_add_f32 v[202:203], v[38:39], v[38:39] op_sel_hi:[0,1]
	v_sub_f32_e32 v38, v208, v75
	v_exp_f32_e32 v204, v38
	v_sub_f32_e32 v38, v209, v75
	v_exp_f32_e32 v208, v38
	v_sub_f32_e32 v38, v206, v75
	v_exp_f32_e32 v205, v38
	v_sub_f32_e32 v38, v207, v75
	v_exp_f32_e32 v209, v38
	s_nop 0
	v_pk_add_f32 v[38:39], v[204:205], v[208:209]
	s_nop 0
	v_pk_add_f32 v[206:207], v[38:39], v[38:39] op_sel_hi:[0,1]
	v_sub_f32_e32 v38, v214, v75
	v_exp_f32_e32 v151, v38
	v_sub_f32_e32 v38, v215, v75
	v_exp_f32_e32 v155, v38
	v_sub_f32_e32 v38, v212, v75
	v_exp_f32_e32 v212, v34
	v_sub_f32_e32 v34, v35, v75
	v_exp_f32_e32 v159, v38
	v_sub_f32_e32 v38, v213, v75
	v_exp_f32_e32 v214, v34
	v_sub_f32_e32 v34, v36, v75
	v_exp_f32_e32 v161, v38
	v_exp_f32_e32 v206, v34
	v_sub_f32_e32 v34, v37, v75
	v_exp_f32_e32 v202, v34
	v_add_f32_e32 v213, v151, v155
	v_add_f32_e32 v215, v159, v161
	v_pk_add_f32 v[34:35], v[212:213], v[214:215]
	v_pk_add_f32 v[36:37], v[206:207], v[202:203]
	v_cvt_pk_bf16_f32 v38, v40, v216
	v_cvt_pk_bf16_f32 v39, v41, v217
	v_cvt_pk_bf16_f32 v40, v44, v220
	v_cvt_pk_bf16_f32 v41, v45, v221
	v_cvt_pk_bf16_f32 v42, v77, v81
	s_nop 0
	v_pk_add_f32 v[34:35], v[34:35], v[36:37]
	v_cvt_pk_bf16_f32 v43, v85, v121
	v_cvt_pk_bf16_f32 v44, v46, v48
	v_cvt_pk_bf16_f32 v45, v222, v218
	v_cvt_pk_bf16_f32 v46, v50, v56
	v_cvt_pk_bf16_f32 v47, v51, v57
	s_nop 0
	v_add_f32_e32 v34, v34, v35
	v_mov_b32_e32 v35, v34
	s_nop 1
	v_permlane16_swap_b32_e32 v35, v34
	s_nop 1
	v_cvt_pk_bf16_f32 v48, v49, v123
	v_cvt_pk_bf16_f32 v49, v127, v131
	v_cvt_pk_bf16_f32 v50, v58, v60
	v_cvt_pk_bf16_f32 v51, v54, v52
	s_waitcnt lgkmcnt(0)
	v_add_f32_e32 v34, v34, v35
	v_mov_b32_e32 v35, v34
	s_nop 1
	v_permlane32_swap_b32_e32 v35, v34
	s_nop 1
	v_cvt_pk_bf16_f32 v52, v152, v156
	v_cvt_pk_bf16_f32 v53, v153, v157
	v_cvt_pk_bf16_f32 v54, v55, v59
	v_cvt_pk_bf16_f32 v55, v61, v135
	s_waitcnt lgkmcnt(0)
	v_add_f32_e32 v34, v34, v35
	v_fma_f32 v35, v90, s65, -v75
	v_exp_f32_e32 v35, v35
	v_cvt_pk_bf16_f32 v56, v158, v160
	v_cvt_pk_bf16_f32 v57, v154, v150
	v_cvt_pk_bf16_f32 v58, v204, v208
	v_cvt_pk_bf16_f32 v59, v205, v209
	v_cvt_pk_bf16_f32 v60, v151, v155
	s_nop 0
	v_add_f32_e32 v75, v35, v34
	v_div_scale_f32 v77, s[0:1], v75, v75, 1.0
	v_rcp_f32_e32 v81, v77
	v_cvt_pk_bf16_f32 v61, v159, v161
	v_cvt_pk_bf16_f32 v34, v212, v214
	v_cvt_pk_bf16_f32 v35, v206, v202
	v_cvt_pk_bf16_f32 v36, v91, v91
	v_cvt_pk_bf16_f32 v37, v91, v91
	s_nop 0
	v_fma_f32 v85, -v77, v81, 1.0
	v_fmac_f32_e32 v81, v85, v81
	v_div_scale_f32 v85, vcc, 1.0, v75, 1.0
	v_mul_f32_e32 v90, v85, v81
	v_fma_f32 v121, -v77, v90, v85
	v_fmac_f32_e32 v90, v121, v81
	v_fma_f32 v77, -v77, v90, v85
	v_div_fmas_f32 v77, v77, v81, v90
	v_div_fixup_f32 v90, v77, v75, 1.0
	v_add_u32_e32 v75, v191, v164
	v_add_u32_e32 v75, 0xd800, v75
	ds_read2_b64 v[150:153], v75 offset0:160 offset1:164
	ds_read2_b64 v[154:157], v75 offset0:168 offset1:172
	s_waitcnt lgkmcnt(1)
	v_mfma_f32_16x16x32_bf16 v[150:153], v[150:153], v[38:41], 0
	s_waitcnt lgkmcnt(0)
	v_mfma_f32_16x16x32_bf16 v[150:153], v[154:157], v[42:45], v[150:153]
	ds_read2_b64 v[154:157], v75 offset0:176 offset1:180
	s_waitcnt lgkmcnt(0)
	v_mfma_f32_16x16x32_bf16 v[150:153], v[154:157], v[46:49], v[150:153]
	ds_read2_b64 v[154:157], v75 offset0:184 offset1:188
	s_waitcnt lgkmcnt(0)
	v_mfma_f32_16x16x32_bf16 v[150:153], v[154:157], v[50:53], v[150:153]
	ds_read2_b64 v[154:157], v75 offset0:192 offset1:196
	s_waitcnt lgkmcnt(0)
	v_mfma_f32_16x16x32_bf16 v[150:153], v[154:157], v[54:57], v[150:153]
	ds_read2_b64 v[154:157], v75 offset0:200 offset1:204
	s_waitcnt lgkmcnt(0)
	v_mfma_f32_16x16x32_bf16 v[150:153], v[154:157], v[58:61], v[150:153]
	ds_read2_b64 v[154:157], v75 offset0:208 offset1:212
	v_add_u32_e32 v75, 0x9000, v190
	ds_read2_b64 v[158:161], v75 offset0:120 offset1:124
	s_waitcnt lgkmcnt(1)
	v_mfma_f32_16x16x32_bf16 v[152:155], v[154:157], v[34:37], v[150:153]
	s_nop 7
	v_pk_mul_f32 v[150:151], v[90:91], v[154:155] op_sel_hi:[0,1]
	ds_read2_b64 v[154:157], v75 offset0:112 offset1:116
	s_waitcnt lgkmcnt(0)
	v_mfma_f32_16x16x32_bf16 v[154:157], v[154:157], v[38:41], 0
	v_mul_f32_e64 v152, v90, v152
	v_mul_f32_e64 v153, v90, v153
	v_mfma_f32_16x16x32_bf16 v[154:157], v[158:161], v[42:45], v[154:157]
	ds_read2_b64 v[158:161], v75 offset0:128 offset1:132
	s_waitcnt lgkmcnt(0)
	v_mfma_f32_16x16x32_bf16 v[154:157], v[158:161], v[46:49], v[154:157]
	ds_read2_b64 v[158:161], v75 offset0:136 offset1:140
	s_waitcnt lgkmcnt(0)
	v_mfma_f32_16x16x32_bf16 v[154:157], v[158:161], v[50:53], v[154:157]
	ds_read2_b64 v[158:161], v75 offset0:144 offset1:148
	s_waitcnt lgkmcnt(0)
	v_mfma_f32_16x16x32_bf16 v[154:157], v[158:161], v[54:57], v[154:157]
	ds_read2_b64 v[158:161], v75 offset0:152 offset1:156
	s_waitcnt lgkmcnt(0)
	v_mfma_f32_16x16x32_bf16 v[154:157], v[158:161], v[58:61], v[154:157]
	ds_read2_b64 v[158:161], v75 offset0:160 offset1:164
	v_add_u32_e32 v75, 0xb000, v190
	ds_read2_b64 v[202:205], v75 offset0:40 offset1:44
	s_waitcnt lgkmcnt(1)
	v_mfma_f32_16x16x32_bf16 v[154:157], v[158:161], v[34:37], v[154:157]
	ds_read2_b64 v[158:161], v75 offset0:32 offset1:36
	s_nop 6
	v_pk_mul_f32 v[154:155], v[90:91], v[154:155] op_sel_hi:[0,1]
	s_waitcnt lgkmcnt(0)
	v_mfma_f32_16x16x32_bf16 v[158:161], v[158:161], v[38:41], 0
	v_mul_f32_e64 v156, v90, v156
	v_mul_f32_e64 v157, v90, v157
	v_mfma_f32_16x16x32_bf16 v[158:161], v[202:205], v[42:45], v[158:161]
	ds_read2_b64 v[202:205], v75 offset0:48 offset1:52
	s_waitcnt lgkmcnt(0)
	v_mfma_f32_16x16x32_bf16 v[158:161], v[202:205], v[46:49], v[158:161]
	ds_read2_b64 v[202:205], v75 offset0:56 offset1:60
	s_waitcnt lgkmcnt(0)
	v_mfma_f32_16x16x32_bf16 v[158:161], v[202:205], v[50:53], v[158:161]
	ds_read2_b64 v[202:205], v75 offset0:64 offset1:68
	s_waitcnt lgkmcnt(0)
	v_mfma_f32_16x16x32_bf16 v[158:161], v[202:205], v[54:57], v[158:161]
	ds_read2_b64 v[202:205], v75 offset0:72 offset1:76
	s_waitcnt lgkmcnt(0)
	v_mfma_f32_16x16x32_bf16 v[158:161], v[202:205], v[58:61], v[158:161]
	ds_read2_b64 v[202:205], v75 offset0:80 offset1:84
	v_add_u32_e32 v75, 0xc800, v190
	s_waitcnt lgkmcnt(0)
	v_mfma_f32_16x16x32_bf16 v[202:205], v[202:205], v[34:37], v[158:161]
	s_nop 7
	v_pk_mul_f32 v[158:159], v[90:91], v[204:205] op_sel_hi:[0,1]
	v_pk_mul_f32 v[160:161], v[90:91], v[202:203] op_sel_hi:[0,1]
	ds_read2_b64 v[202:205], v75 offset0:208 offset1:212
	s_waitcnt lgkmcnt(0)
	v_mfma_f32_16x16x32_bf16 v[38:41], v[202:205], v[38:41], 0
	ds_read2_b64 v[202:205], v75 offset0:216 offset1:220
	s_waitcnt lgkmcnt(0)
	v_mfma_f32_16x16x32_bf16 v[38:41], v[202:205], v[42:45], v[38:41]
	ds_read2_b64 v[42:45], v75 offset0:224 offset1:228
	s_waitcnt lgkmcnt(0)
	v_mfma_f32_16x16x32_bf16 v[38:41], v[42:45], v[46:49], v[38:41]
	ds_read2_b64 v[42:45], v75 offset0:232 offset1:236
	s_waitcnt lgkmcnt(0)
	v_mfma_f32_16x16x32_bf16 v[38:41], v[42:45], v[50:53], v[38:41]
	ds_read2_b64 v[42:45], v75 offset0:240 offset1:244
	s_waitcnt lgkmcnt(0)
	v_mfma_f32_16x16x32_bf16 v[38:41], v[42:45], v[54:57], v[38:41]
	ds_read2_b64 v[42:45], v75 offset0:248 offset1:252
	s_waitcnt lgkmcnt(0)
	v_mfma_f32_16x16x32_bf16 v[38:41], v[42:45], v[58:61], v[38:41]
	v_add_u32_e32 v42, 0xd000, v190
	ds_read2_b64 v[42:45], v42 offset1:4
	s_waitcnt lgkmcnt(0)
	v_mfma_f32_16x16x32_bf16 v[34:37], v[42:45], v[34:37], v[38:41]
	v_mov_b32_e32 v42, v147
	v_mov_b32_e32 v43, v63
	v_pk_mul_f32 v[42:43], v[42:43], v[42:43]
	s_nop 4
	v_pk_mul_f32 v[38:39], v[90:91], v[36:37] op_sel_hi:[0,1]
	v_mov_b32_e32 v36, v149
	v_mov_b32_e32 v37, v65
	v_pk_mul_f32 v[40:41], v[90:91], v[34:35] op_sel_hi:[0,1]
	v_mov_b32_e32 v34, v148
	v_mov_b32_e32 v35, v64
	v_pk_mul_f32 v[36:37], v[36:37], v[36:37]
	s_nop 0
	v_pk_fma_f32 v[34:35], v[34:35], v[34:35], v[36:37]
	v_mov_b32_e32 v36, v146
	v_mov_b32_e32 v37, v62
	v_pk_fma_f32 v[36:37], v[36:37], v[36:37], v[42:43]
	v_pk_mul_f32 v[42:43], v[66:67], v[66:67]
	v_pk_add_f32 v[34:35], v[34:35], v[36:37]
	v_pk_mul_f32 v[36:37], v[68:69], v[68:69]
	v_pk_add_f32 v[34:35], v[34:35], v[34:35] op_sel:[0,1] op_sel_hi:[1,0]
	v_pk_mov_b32 v[44:45], v[42:43], v[36:37] op_sel:[1,0]
	v_mov_b32_e32 v43, v37
	v_pk_add_f32 v[36:37], v[44:45], v[42:43]
	v_mul_f32_e32 v42, v152, v152
	v_mul_f32_e32 v43, v153, v153
	v_pk_add_f32 v[36:37], v[36:37], v[36:37] op_sel:[0,1] op_sel_hi:[1,0]
	v_mov_b32_e32 v35, v42
	v_mov_b32_e32 v37, v43
	v_pk_add_f32 v[34:35], v[34:35], v[36:37]
	v_mul_f32_e32 v36, v73, v73
	v_mul_f32_e32 v42, v71, v71
	v_mul_f32_e32 v44, v150, v150
	v_mul_f32_e32 v45, v151, v151
	v_pk_fma_f32 v[36:37], v[72:73], v[72:73], v[36:37] op_sel_hi:[1,1,0]
	v_pk_fma_f32 v[42:43], v[70:71], v[70:71], v[42:43] op_sel_hi:[1,1,0]
	v_mov_b32_e32 v37, v44
	v_mov_b32_e32 v43, v45
	v_pk_add_f32 v[36:37], v[36:37], v[42:43]
	v_pk_mul_f32 v[42:43], v[154:155], v[154:155]
	v_pk_add_f32 v[34:35], v[34:35], v[36:37]
	v_pk_mul_f32 v[36:37], v[156:157], v[156:157]
	v_pk_add_f32 v[34:35], v[34:35], v[34:35] op_sel:[0,1] op_sel_hi:[1,0]
	v_pk_mov_b32 v[44:45], v[42:43], v[36:37] op_sel:[1,0]
	v_mov_b32_e32 v43, v37
	v_pk_add_f32 v[36:37], v[44:45], v[42:43]
	v_mul_f32_e32 v42, v40, v40
	v_mul_f32_e32 v43, v41, v41
	v_pk_add_f32 v[36:37], v[36:37], v[36:37] op_sel:[0,1] op_sel_hi:[1,0]
	v_mov_b32_e32 v35, v42
	v_mov_b32_e32 v37, v43
	v_pk_add_f32 v[34:35], v[34:35], v[36:37]
	v_mul_f32_e32 v36, v161, v161
	v_mul_f32_e32 v42, v159, v159
	v_mul_f32_e32 v44, v38, v38
	v_mul_f32_e32 v45, v39, v39
	v_pk_fma_f32 v[36:37], v[160:161], v[160:161], v[36:37] op_sel_hi:[1,1,0]
	v_pk_fma_f32 v[42:43], v[158:159], v[158:159], v[42:43] op_sel_hi:[1,1,0]
	v_mov_b32_e32 v37, v44
	v_mov_b32_e32 v43, v45
	v_pk_add_f32 v[36:37], v[36:37], v[42:43]
	s_nop 0
	v_pk_add_f32 v[34:35], v[34:35], v[36:37]
	s_nop 0
	v_add_f32_e32 v34, v34, v35
	v_mov_b32_e32 v35, v34
	s_nop 1
	v_permlane16_swap_b32_e32 v35, v34
	s_nop 1
	s_waitcnt lgkmcnt(0)
	v_add_f32_e32 v34, v34, v35
	v_mov_b32_e32 v35, v34
	s_nop 1
	v_permlane32_swap_b32_e32 v35, v34
	s_nop 1
	s_waitcnt lgkmcnt(0)
	v_add_f32_e32 v34, v34, v35
	s_nop 1
	v_mov_b32_dpp v35, v34 quad_perm:[1,0,3,2] row_mask:0xf bank_mask:0xf
	s_nop 0
	s_waitcnt lgkmcnt(0)
	v_add_f32_e32 v34, v34, v35
	s_nop 1
	v_mov_b32_dpp v35, v34 quad_perm:[2,3,0,1] row_mask:0xf bank_mask:0xf
	s_nop 0
	s_waitcnt lgkmcnt(0)
	v_add_f32_e32 v34, v34, v35
	v_fmamk_f32 v34, v34, 0x3b000000, v185
	v_cmp_gt_f32_e32 vcc, s66, v34
	v_mul_f32_e32 v35, 0x4b800000, v34
	s_nop 0
	v_cndmask_b32_e32 v34, v34, v35, vcc
	v_rsq_f32_e32 v34, v34
	s_nop 0
	v_mul_f32_e32 v35, 0x45800000, v34
	v_cndmask_b32_e32 v42, v34, v35, vcc
	global_load_dwordx4 v[34:37], v[98:99], off
	v_pk_mul_f32 v[44:45], v[148:149], v[42:43] op_sel_hi:[1,0]
	v_pk_mul_f32 v[46:47], v[146:147], v[42:43] op_sel_hi:[1,0]
	v_pk_mul_f32 v[48:49], v[62:63], v[42:43] op_sel_hi:[1,0]
	v_pk_mul_f32 v[40:41], v[40:41], v[42:43] op_sel_hi:[1,0]
	s_waitcnt vmcnt(0)
	v_pk_mul_f32 v[34:35], v[34:35], v[44:45]
	v_pk_mul_f32 v[36:37], v[36:37], v[46:47]
	v_cvt_pk_bf16_f32 v34, v34, v35
	s_nop 0
	v_cvt_pk_bf16_f32 v35, v36, v37
	v_pk_mul_f32 v[36:37], v[64:65], v[42:43] op_sel_hi:[1,0]
	v_pk_mul_f32 v[46:47], v[226:227], v[48:49]
	v_pk_mul_f32 v[36:37], v[224:225], v[36:37]
	v_lshl_add_u64 v[44:45], v[138:139], 0, s[24:25]
	v_cvt_pk_bf16_f32 v36, v36, v37
	v_cvt_pk_bf16_f32 v37, v46, v47
	v_pk_mul_f32 v[46:47], v[68:69], v[42:43] op_sel_hi:[1,0]
	v_permlane16_swap_b32_e32 v34, v36
	v_permlane16_swap_b32_e32 v35, v37
	global_store_dwordx4 v[44:45], v[34:37], off
	s_nop 0
	v_pk_mul_f32 v[44:45], v[66:67], v[42:43] op_sel_hi:[1,0]
	v_pk_mul_f32 v[48:49], v[70:71], v[42:43] op_sel_hi:[1,0]
	v_pk_mul_f32 v[34:35], v[228:229], v[44:45]
	v_pk_mul_f32 v[36:37], v[230:231], v[46:47]
	v_cvt_pk_bf16_f32 v34, v34, v35
	s_nop 0
	v_cvt_pk_bf16_f32 v35, v36, v37
	v_pk_mul_f32 v[36:37], v[72:73], v[42:43] op_sel_hi:[1,0]
	v_pk_mul_f32 v[46:47], v[234:235], v[48:49]
	v_pk_mul_f32 v[36:37], v[232:233], v[36:37]
	v_lshl_add_u64 v[44:45], v[140:141], 0, s[24:25]
	v_cvt_pk_bf16_f32 v36, v36, v37
	v_cvt_pk_bf16_f32 v37, v46, v47
	v_pk_mul_f32 v[46:47], v[150:151], v[42:43] op_sel_hi:[1,0]
	v_permlane16_swap_b32_e32 v34, v36
	v_permlane16_swap_b32_e32 v35, v37
	global_store_dwordx4 v[44:45], v[34:37], off
	s_nop 0
	v_pk_mul_f32 v[44:45], v[152:153], v[42:43] op_sel_hi:[1,0]
	v_pk_mul_f32 v[48:49], v[156:157], v[42:43] op_sel_hi:[1,0]
	v_pk_mul_f32 v[34:35], v[44:45], v[236:237]
	v_pk_mul_f32 v[36:37], v[46:47], v[238:239]
	v_cvt_pk_bf16_f32 v34, v34, v35
	s_nop 0
	v_cvt_pk_bf16_f32 v35, v36, v37
	v_pk_mul_f32 v[36:37], v[154:155], v[42:43] op_sel_hi:[1,0]
	v_pk_mul_f32 v[46:47], v[48:49], v[242:243]
	v_pk_mul_f32 v[36:37], v[36:37], v[240:241]
	v_lshl_add_u64 v[44:45], v[142:143], 0, s[24:25]
	v_cvt_pk_bf16_f32 v36, v36, v37
	v_cvt_pk_bf16_f32 v37, v46, v47
	v_pk_mul_f32 v[46:47], v[158:159], v[42:43] op_sel_hi:[1,0]
	v_permlane16_swap_b32_e32 v34, v36
	v_permlane16_swap_b32_e32 v35, v37
	global_store_dwordx4 v[44:45], v[34:37], off
	s_nop 0
	v_pk_mul_f32 v[44:45], v[160:161], v[42:43] op_sel_hi:[1,0]
	v_pk_mul_f32 v[42:43], v[38:39], v[42:43] op_sel_hi:[1,0]
	v_pk_mul_f32 v[36:37], v[46:47], v[246:247]
	v_pk_mul_f32 v[34:35], v[44:45], v[244:245]
	s_nop 0
	v_cvt_pk_bf16_f32 v34, v34, v35
	v_cvt_pk_bf16_f32 v35, v36, v37
	v_pk_mul_f32 v[38:39], v[42:43], v[250:251]
	v_pk_mul_f32 v[36:37], v[40:41], v[248:249]
	s_nop 0
	v_cvt_pk_bf16_f32 v36, v36, v37
	v_cvt_pk_bf16_f32 v37, v38, v39
	v_lshl_add_u64 v[38:39], v[144:145], 0, s[24:25]
	s_add_u32 s24, s24, 0x2000
	s_addc_u32 s25, s25, 0
	v_permlane16_swap_b32_e32 v34, v36
	v_permlane16_swap_b32_e32 v35, v37
	s_cmpk_eq_i32 s24, 0x4000
	global_store_dwordx4 v[38:39], v[34:37], off
	s_cbranch_scc0 .LBB0_414
	s_mov_b64 s[0:1], 0
